# NSA compressed pass 2: hand-emitted body for fully valid tiles (no validity masks, importance sums via fused v_add_f32_dpp instead of ds_bpermute, in-place registers); partial tiles keep the original
# speedup vs baseline: 1.0132x; 1.0039x over previous
.Lmy_p2fast:
	v_mfma_f32_32x32x16_bf16 v[2:17], v[190:193], v[134:137], v[2:17]
	v_mfma_f32_32x32x16_bf16 v[2:17], v[204:207], v[138:141], v[2:17]
	v_add_f32_e32 v18, v18, v173
	v_add_f32_e32 v19, v19, v173
	v_add_f32_e32 v20, v20, v173
	v_add_f32_e32 v21, v21, v173
	v_add_f32_e32 v22, v22, v173
	v_add_f32_e32 v23, v23, v173
	v_add_f32_e32 v24, v24, v173
	v_add_f32_e32 v25, v25, v173
	v_add_f32_e32 v26, v26, v173
	v_add_f32_e32 v27, v27, v173
	v_add_f32_e32 v28, v28, v173
	v_add_f32_e32 v29, v29, v173
	v_add_f32_e32 v30, v30, v173
	v_add_f32_e32 v31, v31, v173
	v_add_f32_e32 v32, v32, v173
	v_add_f32_e32 v33, v33, v173
	v_exp_f32_e32 v18, v18
	v_exp_f32_e32 v19, v19
	v_exp_f32_e32 v20, v20
	v_exp_f32_e32 v21, v21
	v_exp_f32_e32 v22, v22
	v_exp_f32_e32 v23, v23
	v_exp_f32_e32 v24, v24
	v_exp_f32_e32 v25, v25
	v_exp_f32_e32 v26, v26
	v_exp_f32_e32 v27, v27
	v_exp_f32_e32 v28, v28
	v_exp_f32_e32 v29, v29
	v_exp_f32_e32 v30, v30
	v_exp_f32_e32 v31, v31
	v_exp_f32_e32 v32, v32
	v_exp_f32_e32 v33, v33
	v_pk_mul_f32 v[18:19], v[180:181], v[18:19]
	v_pk_mul_f32 v[20:21], v[180:181], v[20:21]
	v_pk_mul_f32 v[22:23], v[180:181], v[22:23]
	v_pk_mul_f32 v[24:25], v[180:181], v[24:25]
	v_pk_mul_f32 v[26:27], v[180:181], v[26:27]
	v_pk_mul_f32 v[28:29], v[180:181], v[28:29]
	v_pk_mul_f32 v[30:31], v[180:181], v[30:31]
	v_pk_mul_f32 v[32:33], v[180:181], v[32:33]
	v_add_f32_e32 v189, v18, v19
	v_add_f32_e32 v191, v20, v21
	v_add_f32_e32 v193, v22, v23
	v_add_f32_e32 v195, v24, v25
	v_add_f32_e32 v189, v189, v191
	v_add_f32_e32 v193, v193, v195
	s_nop 0
	v_add_f32_dpp v191, v189, v189 quad_perm:[1,0,3,2] row_mask:0xf bank_mask:0xf
	v_add_f32_dpp v190, v21, v21 quad_perm:[1,0,3,2] row_mask:0xf bank_mask:0xf
	v_add_f32_dpp v195, v193, v193 quad_perm:[1,0,3,2] row_mask:0xf bank_mask:0xf
	v_add_f32_dpp v194, v25, v25 quad_perm:[1,0,3,2] row_mask:0xf bank_mask:0xf
	s_nop 0
	v_add_f32_dpp v189, v191, v191 quad_perm:[2,3,0,1] row_mask:0xf bank_mask:0xf
	v_add_f32_dpp v192, v190, v190 quad_perm:[2,3,0,1] row_mask:0xf bank_mask:0xf
	v_add_f32_dpp v193, v195, v195 quad_perm:[2,3,0,1] row_mask:0xf bank_mask:0xf
	v_add_f32_dpp v197, v194, v194 quad_perm:[2,3,0,1] row_mask:0xf bank_mask:0xf
	s_and_saveexec_b64 s[0:1], vcc
	ds_add_f32 v179, v189
	ds_add_f32 v179, v192 offset:4
	ds_add_f32 v179, v193 offset:8
	ds_add_f32 v179, v197 offset:12
	s_or_b64 exec, exec, s[0:1]
	v_add_f32_e32 v189, v26, v27
	v_add_f32_e32 v191, v28, v29
	v_add_f32_e32 v193, v30, v31
	v_add_f32_e32 v195, v32, v33
	v_add_f32_e32 v189, v189, v191
	v_add_f32_e32 v193, v193, v195
	s_nop 0
	v_add_f32_dpp v191, v189, v189 quad_perm:[1,0,3,2] row_mask:0xf bank_mask:0xf
	v_add_f32_dpp v190, v29, v29 quad_perm:[1,0,3,2] row_mask:0xf bank_mask:0xf
	v_add_f32_dpp v195, v193, v193 quad_perm:[1,0,3,2] row_mask:0xf bank_mask:0xf
	v_add_f32_dpp v194, v33, v33 quad_perm:[1,0,3,2] row_mask:0xf bank_mask:0xf
	s_nop 0
	v_add_f32_dpp v189, v191, v191 quad_perm:[2,3,0,1] row_mask:0xf bank_mask:0xf
	v_add_f32_dpp v192, v190, v190 quad_perm:[2,3,0,1] row_mask:0xf bank_mask:0xf
	v_add_f32_dpp v193, v195, v195 quad_perm:[2,3,0,1] row_mask:0xf bank_mask:0xf
	v_add_f32_dpp v197, v194, v194 quad_perm:[2,3,0,1] row_mask:0xf bank_mask:0xf
	s_and_saveexec_b64 s[0:1], vcc
	ds_add_f32 v179, v189 offset:16
	ds_add_f32 v179, v192 offset:20
	ds_add_f32 v179, v193 offset:24
	ds_add_f32 v179, v197 offset:28
	s_or_b64 exec, exec, s[0:1]
	v_add_f32_e32 v2, v2, v173
	v_add_f32_e32 v3, v3, v173
	v_add_f32_e32 v4, v4, v173
	v_add_f32_e32 v5, v5, v173
	v_add_f32_e32 v6, v6, v173
	v_add_f32_e32 v7, v7, v173
	v_add_f32_e32 v8, v8, v173
	v_add_f32_e32 v9, v9, v173
	v_add_f32_e32 v10, v10, v173
	v_add_f32_e32 v11, v11, v173
	v_add_f32_e32 v12, v12, v173
	v_add_f32_e32 v13, v13, v173
	v_add_f32_e32 v14, v14, v173
	v_add_f32_e32 v15, v15, v173
	v_add_f32_e32 v16, v16, v173
	v_add_f32_e32 v17, v17, v173
	v_exp_f32_e32 v2, v2
	v_exp_f32_e32 v3, v3
	v_exp_f32_e32 v4, v4
	v_exp_f32_e32 v5, v5
	v_exp_f32_e32 v6, v6
	v_exp_f32_e32 v7, v7
	v_exp_f32_e32 v8, v8
	v_exp_f32_e32 v9, v9
	v_exp_f32_e32 v10, v10
	v_exp_f32_e32 v11, v11
	v_exp_f32_e32 v12, v12
	v_exp_f32_e32 v13, v13
	v_exp_f32_e32 v14, v14
	v_exp_f32_e32 v15, v15
	v_exp_f32_e32 v16, v16
	v_exp_f32_e32 v17, v17
	v_pk_mul_f32 v[2:3], v[180:181], v[2:3]
	v_pk_mul_f32 v[4:5], v[180:181], v[4:5]
	v_pk_mul_f32 v[6:7], v[180:181], v[6:7]
	v_pk_mul_f32 v[8:9], v[180:181], v[8:9]
	v_pk_mul_f32 v[10:11], v[180:181], v[10:11]
	v_pk_mul_f32 v[12:13], v[180:181], v[12:13]
	v_pk_mul_f32 v[14:15], v[180:181], v[14:15]
	v_pk_mul_f32 v[16:17], v[180:181], v[16:17]
	v_add_f32_e32 v189, v2, v3
	v_add_f32_e32 v191, v4, v5
	v_add_f32_e32 v193, v6, v7
	v_add_f32_e32 v195, v8, v9
	v_add_f32_e32 v189, v189, v191
	v_add_f32_e32 v193, v193, v195
	s_nop 0
	v_add_f32_dpp v191, v189, v189 quad_perm:[1,0,3,2] row_mask:0xf bank_mask:0xf
	v_add_f32_dpp v190, v5, v5 quad_perm:[1,0,3,2] row_mask:0xf bank_mask:0xf
	v_add_f32_dpp v195, v193, v193 quad_perm:[1,0,3,2] row_mask:0xf bank_mask:0xf
	v_add_f32_dpp v194, v9, v9 quad_perm:[1,0,3,2] row_mask:0xf bank_mask:0xf
	s_nop 0
	v_add_f32_dpp v189, v191, v191 quad_perm:[2,3,0,1] row_mask:0xf bank_mask:0xf
	v_add_f32_dpp v192, v190, v190 quad_perm:[2,3,0,1] row_mask:0xf bank_mask:0xf
	v_add_f32_dpp v193, v195, v195 quad_perm:[2,3,0,1] row_mask:0xf bank_mask:0xf
	v_add_f32_dpp v197, v194, v194 quad_perm:[2,3,0,1] row_mask:0xf bank_mask:0xf
	s_and_saveexec_b64 s[0:1], vcc
	ds_add_f32 v179, v189 offset:32
	ds_add_f32 v179, v192 offset:36
	ds_add_f32 v179, v193 offset:40
	ds_add_f32 v179, v197 offset:44
	s_or_b64 exec, exec, s[0:1]
	v_add_f32_e32 v189, v10, v11
	v_add_f32_e32 v191, v12, v13
	v_add_f32_e32 v193, v14, v15
	v_add_f32_e32 v195, v16, v17
	v_add_f32_e32 v189, v189, v191
	v_add_f32_e32 v193, v193, v195
	s_nop 0
	v_add_f32_dpp v191, v189, v189 quad_perm:[1,0,3,2] row_mask:0xf bank_mask:0xf
	v_add_f32_dpp v190, v13, v13 quad_perm:[1,0,3,2] row_mask:0xf bank_mask:0xf
	v_add_f32_dpp v195, v193, v193 quad_perm:[1,0,3,2] row_mask:0xf bank_mask:0xf
	v_add_f32_dpp v194, v17, v17 quad_perm:[1,0,3,2] row_mask:0xf bank_mask:0xf
	s_nop 0
	v_add_f32_dpp v189, v191, v191 quad_perm:[2,3,0,1] row_mask:0xf bank_mask:0xf
	v_add_f32_dpp v192, v190, v190 quad_perm:[2,3,0,1] row_mask:0xf bank_mask:0xf
	v_add_f32_dpp v193, v195, v195 quad_perm:[2,3,0,1] row_mask:0xf bank_mask:0xf
	v_add_f32_dpp v197, v194, v194 quad_perm:[2,3,0,1] row_mask:0xf bank_mask:0xf
	v_add_u32_e32 v196, s13, v188
	v_add_u32_e32 v196, 14, v196
	v_cmp_gt_u32_e64 s[40:41], s17, v196
	s_and_saveexec_b64 s[0:1], vcc
	ds_add_f32 v179, v189 offset:48
	ds_add_f32 v179, v192 offset:52
	ds_add_f32 v179, v193 offset:56
	s_and_b64 exec, exec, s[40:41]
	ds_add_f32 v179, v197 offset:60
	s_or_b64 exec, exec, s[0:1]
	v_cvt_pk_bf16_f32 v18, v18, v19
	v_cvt_pk_bf16_f32 v19, v20, v21
	v_cvt_pk_bf16_f32 v20, v22, v23
	v_cvt_pk_bf16_f32 v21, v24, v25
	v_cvt_pk_bf16_f32 v22, v26, v27
	v_cvt_pk_bf16_f32 v23, v28, v29
	v_cvt_pk_bf16_f32 v24, v30, v31
	v_cvt_pk_bf16_f32 v25, v32, v33
	v_cvt_pk_bf16_f32 v2, v2, v3
	v_cvt_pk_bf16_f32 v3, v4, v5
	v_cvt_pk_bf16_f32 v4, v6, v7
	v_cvt_pk_bf16_f32 v5, v8, v9
	v_cvt_pk_bf16_f32 v6, v10, v11
	v_cvt_pk_bf16_f32 v7, v12, v13
	v_cvt_pk_bf16_f32 v8, v14, v15
	v_cvt_pk_bf16_f32 v9, v16, v17
	s_waitcnt vmcnt(15)
	v_mfma_f32_32x32x16_bf16 v[34:49], v[166:169], v[18:21], v[34:49]
	s_waitcnt vmcnt(11)
	v_mfma_f32_32x32x16_bf16 v[50:65], v[150:153], v[18:21], v[50:65]
	s_add_i32 s13, s13, 16
	v_add_u32_e32 v179, 64, v179
	v_add_u32_e32 v170, 0x400, v170
	v_lshl_add_u64 v[182:183], v[182:183], 0, s[10:11]
	v_mfma_f32_32x32x16_bf16 v[34:49], v[162:165], v[22:25], v[34:49]
	s_cmp_eq_u32 s14, s13
	s_waitcnt vmcnt(10)
	v_mfma_f32_32x32x16_bf16 v[50:65], v[154:157], v[22:25], v[50:65]
	v_mfma_f32_32x32x16_bf16 v[34:49], v[158:161], v[2:5], v[34:49]
	s_waitcnt vmcnt(9)
	v_mfma_f32_32x32x16_bf16 v[50:65], v[146:149], v[2:5], v[50:65]
	v_mfma_f32_32x32x16_bf16 v[34:49], v[142:145], v[6:9], v[34:49]
	s_waitcnt vmcnt(8)
	v_mfma_f32_32x32x16_bf16 v[50:65], v[126:129], v[6:9], v[50:65]
	s_cbranch_scc1 .LBB0_268
	s_branch .LBB0_244

.LBB0_244:
	s_waitcnt vmcnt(7)
	v_mfma_f32_32x32x16_bf16 v[18:33], v[114:117], v[90:93], 0
	s_mov_b32 s0, s15
	s_add_i32 s15, s15, 1
	s_cmp_lt_u32 s15, s12
	s_waitcnt vmcnt(1) lgkmcnt(0)
	v_mov_b64_e32 v[192:193], v[120:121]
	s_cselect_b32 s94, s15, s0
	v_mov_b64_e32 v[190:191], v[118:119]
	v_mov_b64_e32 v[120:121], v[104:105]
	v_mfma_f32_32x32x16_bf16 v[18:33], v[94:97], v[130:133], v[18:33]
	s_lshl_b64 s[0:1], s[94:95], 13
	v_mov_b64_e32 v[118:119], v[102:103]
	v_add_co_u32_e64 v102, s[40:41], s33, v182
	s_add_u32 s0, s42, s0
	v_mov_b64_e32 v[218:219], v[112:113]
	v_addc_co_u32_e64 v103, s[40:41], 0, v183, s[40:41]
	v_mfma_f32_32x32x16_bf16 v[18:33], v[98:101], v[134:137], v[18:33]
	s_addc_u32 s1, s43, s1
	v_mov_b64_e32 v[216:217], v[110:111]
	global_load_dwordx4 v[166:169], v[182:183], off
	global_load_dwordx4 v[162:165], v[182:183], off offset:1024
	global_load_dwordx4 v[158:161], v[182:183], off offset:2048
	global_load_dwordx4 v[142:145], v[182:183], off offset:3072
	global_load_dwordx4 v[150:153], v[102:103], off
	global_load_dwordx4 v[154:157], v[102:103], off offset:1024
	global_load_dwordx4 v[146:149], v[102:103], off offset:2048
	global_load_dwordx4 v[126:129], v[102:103], off offset:3072
	s_waitcnt vmcnt(8)
	v_mov_b64_e32 v[206:207], v[124:125]
	v_mov_b64_e32 v[204:205], v[122:123]
	v_or_b32_e32 v189, 47, v170
	v_mfma_f32_32x32x16_bf16 v[2:17], v[106:109], v[90:93], 0
	global_load_dwordx4 v[114:117], v0, s[0:1]
	global_load_dwordx4 v[94:97], v0, s[0:1] offset:1024
	global_load_dwordx4 v[98:101], v0, s[0:1] offset:2048
	global_load_dwordx4 v[102:105], v0, s[0:1] offset:3072
	global_load_dwordx4 v[106:109], v172, s[0:1]
	global_load_dwordx4 v[110:113], v174, s[0:1]
	v_or_b32_e32 v196, 31, v170
	v_cmp_le_i32_e64 s[40:41], v189, v171
	v_add_u32_e32 v189, 63, v170
	v_mfma_f32_32x32x16_bf16 v[18:33], v[118:121], v[138:141], v[18:33]
	global_load_dwordx4 v[118:121], v176, s[0:1]
	global_load_dwordx4 v[122:125], v178, s[0:1]
	v_mfma_f32_32x32x16_bf16 v[2:17], v[216:219], v[130:133], v[2:17]
	s_nop 8
	v_add_u32_e32 v197, 0x3cf, v170
	v_cmp_gt_i32_e64 s[0:1], v197, v200
	s_cmp_lg_u64 s[0:1], 0
	s_cbranch_scc0 .Lmy_p2fast
	v_add_f32_e32 v18, v18, v173
	v_add_f32_e32 v19, v19, v173
	v_exp_f32_e32 v18, v18
	v_exp_f32_e32 v19, v19
	v_add_f32_e32 v21, v21, v173
	v_pk_mul_f32 v[194:195], v[180:181], v[18:19]
	v_add_f32_e32 v19, v20, v173
	v_exp_f32_e32 v19, v19
	v_mfma_f32_32x32x16_bf16 v[2:17], v[190:193], v[134:137], v[2:17]
	v_exp_f32_e32 v190, v21
	v_cndmask_b32_e64 v18, 0, v195, s[40:41]
	v_cmp_le_i32_e64 s[40:41], v196, v200
	v_mul_f32_e32 v19, v180, v19
	s_nop 0
	v_cndmask_b32_e64 v20, 0, v194, s[40:41]
	v_cmp_le_i32_e64 s[40:41], v189, v200
	v_mul_f32_e32 v189, v180, v190
	v_mfma_f32_32x32x16_bf16 v[2:17], v[204:207], v[138:141], v[2:17]
	v_cndmask_b32_e64 v21, 0, v19, s[40:41]
	v_add_u32_e32 v19, 0x4f, v170
	v_cmp_le_i32_e64 s[40:41], v19, v200
	v_add_f32_e32 v19, v20, v18
	s_nop 0
	v_cndmask_b32_e64 v189, 0, v189, s[40:41]
	v_add_f32_e32 v190, v21, v189
	v_add_f32_e32 v19, v19, v190
	ds_bpermute_b32 v190, v175, v19
	ds_bpermute_b32 v191, v175, v189
	s_waitcnt lgkmcnt(1)
	v_add_f32_e32 v193, v19, v190
	s_waitcnt lgkmcnt(0)
	v_add_f32_e32 v191, v189, v191
	ds_bpermute_b32 v197, v177, v193
	ds_bpermute_b32 v192, v177, v191
	v_mov_b32_e32 v19, v170
	v_add_u32_e32 v190, s13, v188
	s_and_saveexec_b64 s[0:1], vcc
	s_cbranch_execz .LBB0_247
	s_waitcnt lgkmcnt(1)
	v_add_f32_e32 v193, v193, v197
	ds_add_f32 v179, v193
	v_cmp_gt_u32_e64 s[40:41], s17, v190
	s_and_b64 exec, exec, s[40:41]
	s_cbranch_execz .LBB0_247
	s_waitcnt lgkmcnt(1)
	v_add_f32_e32 v191, v191, v192
	ds_add_f32 v179, v191 offset:4
